# v019 plus per-XCD 1us staggered start of the residual GEMM phases (out-proj, down-proj)
# baseline (speedup 1.0000x reference)
; __global__ void __launch_bounds__(512, 2) mega(Args a) {
;     ...
;         for (int st = 0; st < 3; ++st) {
;             PH_BEGIN {
;                 if (st == 1) {
;                     pg8::Gemm g{xb, (const bf16_t*)(ws + WS_WUP + (size_t)L * 32 * MiB), M, FF, D}; pg8::StaticOrder S; S.init(M, FF, G, (int)blockIdx.x);
;                     pg8::EpiUp E{hid, ss + (size_t)(2 * L + 1) * M, FF};
;     ...
;                     for (int rep_ = 0; rep_ < REP_GUP; ++rep_) pg8::gemm_phase<pg8::EpiUp, pg8::StaticOrder, PG8_ALIGN, PG8_SP2>(lds, g, S, E);
;     ...
;                 } else {
;                     const bf16_t* Am = (st == 0) ? att : hid; const int Kd = (st == 0) ? D : FF;
;                     const bf16_t* Bm = (st == 0) ? (const bf16_t*)(ws + WS_WOUT + (size_t)L * 8 * MiB) : (const bf16_t*)(ws + WS_WDN + (size_t)L * 32 * MiB);
;                     pg8::Gemm g{Am, Bm, M, D, Kd}; pg8::StaticOrder S; S.init(M, D, G, (int)blockIdx.x);
;                     const bool lastres = (st == 2 && L == NLAYER - 1);
;                     pg8::EpiRes E{(st == 0) ? xin : a.out, lastres ? nullptr : a.out, xb, ss + (size_t)(2 * L + 1 + (st == 2 ? 1 : 0)) * M};
;     ...
;                     pg8::gemm_phase<pg8::EpiRes, pg8::StaticOrder, PG8_ALIGN, PG8_SP2>(lds, g, S, E);
.LBB0_1412:
	s_cmp_ge_i32 s38, s18
	s_cselect_b64 s[0:1], -1, 0
	s_cmp_lt_i32 s38, s19
	s_cselect_b64 s[14:15], -1, 0
	s_and_b64 s[0:1], s[0:1], s[14:15]
	s_mov_b32 s78, s38
	s_andn2_b64 vcc, exec, s[0:1]
	s_cbranch_vccnz .LBB0_1568
	v_mov_b32_e32 v0, v170
	s_cmp_lg_u32 s77, 1
	s_mov_b64 s[0:1], -1
	s_cbranch_scc0 .LBB0_1483
	v_readlane_b32 s0, v249, 31
	v_mov_b32_e32 v14, v171
	v_readlane_b32 s1, v249, 32
	s_andn2_b64 vcc, exec, s[0:1]
	v_readfirstlane_b32 s24, v14
	s_cbranch_vccnz .LBB0_1482
	s_and_b32 s98, s2, 7
	s_cmp_eq_u32 s98, 0
	s_cbranch_scc1 .Lstag_res_done

; #define PG8_STAGE(bufoff, gbase, voff) do { _Pragma("unroll") for (int _i = 0; _i < 2; ++_i) \
;         __builtin_amdgcn_global_load_lds((const unsigned*)((const char*)(gbase) + (voff)[_i]), (PG8_LAS unsigned*)(lds + (bufoff) + ldsw + _i * 8192), 16, 0, 0); } while (0)
; #define PG8_WAIT_V(n) asm volatile("s_waitcnt vmcnt(" #n ")" ::: "memory")
; #define PG8_BAR __builtin_amdgcn_s_barrier()
; template <class Epi, class Sched, bool ALIGN_EPI = false, bool SP2 = false>
; __device__ __forceinline__ void gemm_phase(PG8_LAS unsigned char* lds, const Gemm g, const Sched& S, const Epi& E) {
;     ...
;     unsigned voffA[2], voffB[2];
; #pragma unroll
;     for (int i = 0; i < 2; ++i) { int R, C; stage_rc(tid * 16 + i * 8192, R, C); const int Rb = Epi::PERM ? ((R & ~31) + perm32(R & 31)) : R;
;         voffA[i] = (unsigned)(R * K + C) * 2u; voffB[i] = (unsigned)(Rb * K + C) * 2u; }
;     const size_t kstep = (size_t)(BK * 2);
;     const size_t hstep = (size_t)HALF * K * 2;
;     const size_t tstep = 2 * hstep;
;     const unsigned ldsw = (unsigned)wid * 1024u;
;     const int aoff = lds_byte(wr * 64 + fr, fq * 8), boff = lds_byte(wc * 32 + fr, fq * 8);
;     ...
;     Unit cur, nxt; int ui = 0;
;     if (!S.next(0, cur)) return;
;     f32x4 acc[2][2][4][2];
; #pragma unroll
;     for (int a = 0; a < 2; ++a)
; #pragma unroll
;         for (int b = 0; b < 2; ++b)
; #pragma unroll
;             for (int m = 0; m < 4; ++m)
; #pragma unroll
;                 for (int n = 0; n < 2; ++n) acc[a][b][m][n] = (f32x4){0.f, 0.f, 0.f, 0.f};
;     bf16x8 At[4][2], B0[2][2], B1[2][2];
;     const char* cA = (const char*)g.A + (size_t)cur.pm * tstep; const char* cB = (const char*)g.Bt + (size_t)cur.pn * tstep;
;     S.a_ready(cur);
;     if constexpr (SP2) {
;         PG8_STAGE(PG8_SB(0, 0), cB, voffB); PG8_STAGE(PG8_SB(0, 1), cB + hstep, voffB); PG8_STAGE(PG8_SA(0, 0), cA, voffA); PG8_STAGE(PG8_SA(0, 1), cA + hstep, voffA);
;         if (wr == 1) PG8_BAR;
;         PG8_WAIT_V(2); PG8_BAR;
.Lstag_res_done:
	v_lshlrev_b32_e32 v0, 4, v14
	s_waitcnt vmcnt(1)
	v_add_u32_e32 v2, 0x2000, v0
	v_ashrrev_i32_e32 v3, 31, v2
	v_lshrrev_b32_e32 v3, 22, v3
	v_add_u32_e32 v3, v2, v3
	v_ashrrev_i32_e32 v3, 10, v3
	v_mul_i32_i24_e32 v4, 0x400, v3
	v_sub_u32_e32 v2, v2, v4
	v_lshrrev_b32_e32 v4, 4, v2
	v_bitop3_b32 v2, v4, v2, 32 bitop3:0x6c
	v_ashrrev_i32_e32 v4, 31, v2
	v_lshrrev_b32_e32 v4, 26, v4
	v_add_u32_e32 v4, v2, v4
	s_waitcnt vmcnt(0)
	v_lshlrev_b32_e32 v6, 3, v3
	s_ashr_i32 s40, s24, 8
	s_ashr_i32 s25, s24, 6
	v_readlane_b32 s0, v250, 11
	v_ashrrev_i32_e32 v5, 6, v4
	v_and_b32_e32 v6, -16, v6
	s_cmp_eq_u32 s77, 0
	v_readlane_b32 s1, v250, 12
	v_add_u32_e32 v6, v5, v6
	s_cselect_b32 s38, s1, s23
	s_cselect_b32 s39, s0, s22
	s_movk_i32 s0, 0x2000
	v_and_b32_e32 v5, 3, v5
	s_mov_b32 s1, 0x7fffffe0
	v_lshrrev_b32_e32 v7, 2, v6
	v_lshlrev_b32_e32 v8, 1, v6
	v_and_b32_e32 v4, 0xc0, v4
	s_cselect_b32 s41, 0x800, s0
	v_readlane_b32 s0, v248, 32
	v_and_or_b32 v5, v6, s1, v5
	v_and_b32_e32 v7, 4, v7
	v_and_b32_e32 v8, 24, v8
	v_lshlrev_b32_e32 v3, 5, v3
	v_sub_u32_e32 v2, v2, v4
	s_cselect_b32 s80, s68, s0
	s_cselect_b32 s0, 11, 13
	v_or3_b32 v5, v5, v7, v8
	v_and_b32_e32 v3, 32, v3
	v_ashrrev_i16_sdwa v2, v225, sext(v2) dst_sel:DWORD dst_unused:UNUSED_PAD src0_sel:DWORD src1_sel:BYTE_0
	v_lshlrev_b32_e32 v5, s0, v5
	v_add_u32_sdwa v2, v3, sext(v2) dst_sel:DWORD dst_unused:UNUSED_PAD src0_sel:DWORD src1_sel:WORD_0
	v_lshlrev_b32_e32 v3, s0, v6
	v_add_lshl_u32 v154, v5, v2, 1
	v_add_lshl_u32 v156, v2, v3, 1
	v_bfe_i32 v2, v14, 27, 1
	v_lshrrev_b32_e32 v2, 22, v2
	v_add_u32_e32 v2, v0, v2
	v_and_b32_e32 v2, 0xfffffc00, v2
	v_sub_u32_e32 v0, v0, v2
	v_lshrrev_b32_e32 v2, 4, v0
	v_ashrrev_i32_e32 v4, 31, v14
	v_bitop3_b32 v0, v2, v0, 32 bitop3:0x6c
	v_lshrrev_b32_e32 v4, 26, v4
	v_ashrrev_i32_e32 v2, 31, v0
	v_add_u32_e32 v4, v14, v4
	v_lshrrev_b32_e32 v2, 26, v2
	v_ashrrev_i32_e32 v4, 6, v4
	v_add_u32_e32 v2, v0, v2
	v_lshlrev_b32_e32 v5, 3, v4
	v_ashrrev_i32_e32 v3, 6, v2
	v_and_b32_e32 v5, -16, v5
	v_add_u32_e32 v5, v3, v5
	v_and_b32_e32 v3, 3, v3
	v_lshrrev_b32_e32 v6, 2, v5
	v_lshlrev_b32_e32 v7, 1, v5
	v_and_b32_e32 v2, 0xc0, v2
	v_and_or_b32 v3, v5, s1, v3
	v_and_b32_e32 v6, 4, v6
	v_and_b32_e32 v7, 24, v7
	v_lshlrev_b32_e32 v4, 5, v4
	v_sub_u32_e32 v0, v0, v2
	v_or3_b32 v3, v3, v6, v7
	v_and_b32_e32 v4, 32, v4
	v_ashrrev_i16_sdwa v0, v225, sext(v0) dst_sel:DWORD dst_unused:UNUSED_PAD src0_sel:DWORD src1_sel:BYTE_0
	v_lshlrev_b32_e32 v3, s0, v3
	v_add_u32_sdwa v2, v4, sext(v0) dst_sel:DWORD dst_unused:UNUSED_PAD src0_sel:DWORD src1_sel:WORD_0
	v_add_lshl_u32 v0, v3, v2, 1
	v_lshlrev_b32_e32 v3, s0, v5
	v_readlane_b32 s0, v249, 59
	v_readlane_b32 s14, v249, 61
	s_cselect_b32 s81, 20, 22
	v_readlane_b32 s1, v249, 60
	v_readlane_b32 s15, v249, 62
	s_cselect_b32 s58, s69, s59
	s_lshl_b32 s70, s41, 8
	s_lshl_b32 s82, s25, 10
	s_lshl_b64 s[0:1], s[0:1], s81
	s_lshl_b64 s[14:15], s[14:15], s81
	s_add_u32 s74, s80, s14
	s_addc_u32 s75, s58, s15
	s_add_i32 s83, s82, 0
	s_add_i32 m0, s83, 0x10000
	v_add_lshl_u32 v158, v2, v3, 1
	global_load_lds_dwordx4 v0, s[74:75]
	s_add_i32 m0, s83, 0x12000
	s_add_u32 s14, s74, s70
	global_load_lds_dwordx4 v154, s[74:75]
	s_addc_u32 s15, s75, 0
	s_add_i32 m0, s83, 0x14000
	v_mov_b32_e32 v155, v1
	global_load_lds_dwordx4 v0, s[14:15]
	s_add_i32 m0, s83, 0x16000
	s_add_u32 s44, s39, s0
	s_addc_u32 s45, s38, s1
	s_add_i32 s84, s83, 0x2000
	global_load_lds_dwordx4 v154, s[14:15]
	s_mov_b32 m0, s83
	s_add_u32 s0, s44, s70
	global_load_lds_dwordx4 v158, s[44:45]
	s_mov_b32 m0, s84
	s_addc_u32 s1, s45, 0
	s_add_i32 s85, s83, 0x4000
	global_load_lds_dwordx4 v156, s[44:45]
	s_mov_b32 m0, s85
	s_add_i32 s86, s83, 0x6000
	global_load_lds_dwordx4 v158, s[0:1]
	s_mov_b32 m0, s86
	v_mov_b32_e32 v159, v1
	global_load_lds_dwordx4 v156, s[0:1]
	v_mov_b32_e32 v157, v1
	s_cmp_eq_u32 s40, 1
	v_lshl_add_u64 v[2:3], s[74:75], 0, v[0:1]
	v_lshl_add_u64 v[4:5], s[74:75], 0, v[154:155]
	v_lshl_add_u64 v[6:7], s[14:15], 0, v[0:1]
	v_lshl_add_u64 v[8:9], s[14:15], 0, v[154:155]
	v_lshl_add_u64 v[10:11], s[44:45], 0, v[158:159]
	v_lshl_add_u64 v[12:13], s[44:45], 0, v[156:157]
	s_cselect_b64 s[0:1], -1, 0
	s_cmp_lg_u32 s40, 1
	s_cbranch_scc1 .LBB0_1417
	s_barrier
